# all four GEMM phases: next unit's tile coordinates by increment (static order is a fixed stride in the swizzled tile id), replacing the per-unit division emulation
# speedup vs baseline: 1.0065x; 1.0065x over previous
;     __host__ __device__ bool next(int i, Unit& u) const { Unit m; if (!S.next(i >> 1, m)) return false; u.pm = m.pm + (i & 1) * dpm; u.pn = m.pn + (i & 1) * dpn; return true; }
;     __host__ __device__ bool next(int i, Unit& u) const {
;         const long L = (long)i * G + c; if (L >= nwg) return false;
;         int wgid = (int)L; { const int q = nwg / NXCD, r = nwg % NXCD, xcd = wgid % NXCD, off = wgid / NXCD; wgid = (xcd < r ? xcd * (q + 1) : r * (q + 1) + (xcd - r) * q) + off; }
;         const int nig = WGM * nN, gid = wgid / nig, fm = gid * WGM, gsz = (nM - fm) < WGM ? (nM - fm) : WGM;
;         u.pm = fm + ((wgid % nig) % gsz); u.pn = (wgid % nig) / gsz; return true;
;     }
;     __host__ __device__ bool next(int i, Unit& u) const { Unit m; if (!S.next(i >> 1, m)) return false; u.pm = m.pm; u.pn = m.pn + 4 * (i & 1); return true; }
.LBB0_367:
	s_add_i32 s68, s68, 1
	s_lshr_b32 s6, s68, 1
	s_mul_hi_i32 s7, s6, s26
	s_mul_i32 s6, s6, s26
	s_add_u32 s20, s6, s2
	s_addc_u32 s21, s7, s27
	v_mov_b64_e32 v[0:1], 0x200
	v_cmp_lt_i64_e64 s[6:7], s[20:21], v[0:1]
	v_mov_b64_e32 v[0:1], 0x1ff
	v_cmp_gt_i64_e32 vcc, s[20:21], v[0:1]
	s_cbranch_vccnz .LBB0_373
	s_add_i32 s16, s70, 4
	s_add_i32 s21, s70, -4
	s_add_i32 s22, s69, 8
	s_bitcmp1_b32 s68, 0
	s_cselect_b32 s16, s16, s21
	s_cselect_b32 s18, s69, s22

;     __host__ __device__ bool next(int i, Unit& u) const { Unit m; if (!S.next(i >> 1, m)) return false; u.pm = m.pm; u.pn = m.pn + 4 * (i & 1); return true; }
;     __host__ __device__ bool next(int i, Unit& u) const {
;         const long L = (long)i * G + c; if (L >= nwg) return false;
;         int wgid = (int)L; { const int q = nwg / NXCD, r = nwg % NXCD, xcd = wgid % NXCD, off = wgid / NXCD; wgid = (xcd < r ? xcd * (q + 1) : r * (q + 1) + (xcd - r) * q) + off; }
;         const int nig = WGM * nN, gid = wgid / nig, fm = gid * WGM, gsz = (nM - fm) < WGM ? (nM - fm) : WGM;
;         u.pm = fm + ((wgid % nig) % gsz); u.pn = (wgid % nig) / gsz; return true;
;     }
;     __host__ __device__ bool next(int i, Unit& u) const { Unit m; if (!S.next(i >> 1, m)) return false; u.pm = m.pm + (i & 1) * dpm; u.pn = m.pn + (i & 1) * dpn; return true; }
.LBB0_388:
	s_add_i32 s49, s49, 1
	s_lshr_b32 s6, s49, 1
	s_mul_hi_i32 s7, s6, s26
	s_mul_i32 s6, s6, s26
	s_add_u32 s18, s6, s2
	s_addc_u32 s19, s7, s27
	v_mov_b64_e32 v[0:1], 0x200
	v_cmp_lt_i64_e64 s[6:7], s[18:19], v[0:1]
	v_mov_b64_e32 v[0:1], 0x1ff
	v_cmp_gt_i64_e32 vcc, s[18:19], v[0:1]
	s_cbranch_vccnz .LBB0_394
	s_add_i32 s14, s68, 0x140
	s_add_i32 s16, s60, 8
	s_add_i32 s15, s68, 0xfffffec8
	s_add_i32 s17, s60, -8
	s_bitcmp1_b32 s49, 0
	s_cselect_b32 s14, s14, s15
	s_cselect_b32 s16, s16, s17
